# S5 pass 2: the eight state-row LDS reads of the C*h MFMA chain issued together with counted waits (was two-buffer ping-pong)
# speedup vs baseline: 1.0021x; 1.0021x over previous
.LBB0_921:
	v_lshl_add_u64 v[136:137], v[132:133], 0, s[2:3]
	v_mfma_f32_32x32x16_bf16 v[32:47], v[48:51], v[64:67], 0
	s_mov_b32 s4, 0xc800000
	s_add_u32 s2, s2, 0x20000
	s_addc_u32 s3, s3, 0
	s_cmp_lg_u32 s2, 0x200000
	v_mfma_f32_32x32x16_bf16 v[16:31], v[48:51], v[68:71], 0
	v_mfma_f32_32x32x16_bf16 v[0:15], v[48:51], v[72:75], 0
	v_mfma_f32_32x32x16_bf16 v[48:63], v[48:51], v[76:79], 0
	s_nop 9
	v_permlane32_swap_b32_e32 v32, v16
	v_permlane32_swap_b32_e32 v33, v17
	v_permlane32_swap_b32_e32 v34, v18
	v_permlane32_swap_b32_e32 v35, v19
	v_permlane32_swap_b32_e32 v36, v20
	v_permlane32_swap_b32_e32 v37, v21
	v_permlane32_swap_b32_e32 v38, v22
	v_permlane32_swap_b32_e32 v39, v23
	v_permlane32_swap_b32_e32 v40, v24
	v_permlane32_swap_b32_e32 v41, v25
	v_permlane32_swap_b32_e32 v42, v26
	v_permlane32_swap_b32_e32 v43, v27
	v_permlane32_swap_b32_e32 v44, v28
	v_permlane32_swap_b32_e32 v45, v29
	v_permlane32_swap_b32_e32 v46, v30
	v_permlane32_swap_b32_e32 v47, v31
	v_permlane32_swap_b32_e32 v0, v48
	v_permlane32_swap_b32_e32 v1, v49
	v_permlane32_swap_b32_e32 v2, v50
	v_permlane32_swap_b32_e32 v3, v51
	v_permlane32_swap_b32_e32 v4, v52
	v_permlane32_swap_b32_e32 v5, v53
	v_permlane32_swap_b32_e32 v6, v54
	v_permlane32_swap_b32_e32 v7, v55
	v_permlane32_swap_b32_e32 v8, v56
	v_permlane32_swap_b32_e32 v9, v57
	v_permlane32_swap_b32_e32 v10, v58
	v_permlane32_swap_b32_e32 v11, v59
	v_permlane32_swap_b32_e32 v12, v60
	v_permlane32_swap_b32_e32 v13, v61
	v_permlane32_swap_b32_e32 v14, v62
	v_permlane32_swap_b32_e32 v15, v63
	v_fma_f32 v32, -v125, v142, v32
	v_fma_f32 v0, v125, v143, v0
	v_fmac_f32_e32 v32, v124, v143
	v_fmac_f32_e32 v0, v124, v142
	v_cvt_pk_bf16_f32 v154, v32, v0
	ds_write_b32 v150, v154 offset:8192
	v_fma_f32 v33, -v125, v0, v33
	v_fma_f32 v1, v125, v32, v1
	v_fmac_f32_e32 v33, v124, v32
	v_fmac_f32_e32 v1, v124, v0
	v_cvt_pk_bf16_f32 v154, v33, v1
	ds_write_b32 v150, v154 offset:8464
	v_fma_f32 v34, -v125, v1, v34
	v_fma_f32 v2, v125, v33, v2
	v_fmac_f32_e32 v34, v124, v33
	v_fmac_f32_e32 v2, v124, v1
	v_cvt_pk_bf16_f32 v154, v34, v2
	ds_write_b32 v150, v154 offset:8736
	v_fma_f32 v35, -v125, v2, v35
	v_fma_f32 v3, v125, v34, v3
	v_fmac_f32_e32 v35, v124, v34
	v_fmac_f32_e32 v3, v124, v2
	v_cvt_pk_bf16_f32 v154, v35, v3
	ds_write_b32 v150, v154 offset:9008
	v_fma_f32 v16, -v125, v3, v16
	v_fma_f32 v48, v125, v35, v48
	v_fmac_f32_e32 v16, v124, v35
	v_fmac_f32_e32 v48, v124, v3
	v_cvt_pk_bf16_f32 v154, v16, v48
	ds_write_b32 v150, v154 offset:9280
	v_fma_f32 v17, -v125, v48, v17
	v_fma_f32 v49, v125, v16, v49
	v_fmac_f32_e32 v17, v124, v16
	v_fmac_f32_e32 v49, v124, v48
	v_cvt_pk_bf16_f32 v154, v17, v49
	ds_write_b32 v150, v154 offset:9552
	v_fma_f32 v18, -v125, v49, v18
	v_fma_f32 v50, v125, v17, v50
	v_fmac_f32_e32 v18, v124, v17
	v_fmac_f32_e32 v50, v124, v49
	v_cvt_pk_bf16_f32 v154, v18, v50
	ds_write_b32 v150, v154 offset:9824
	v_fma_f32 v19, -v125, v50, v19
	v_fma_f32 v51, v125, v18, v51
	v_fmac_f32_e32 v19, v124, v18
	v_fmac_f32_e32 v51, v124, v50
	v_cvt_pk_bf16_f32 v154, v19, v51
	ds_write_b32 v150, v154 offset:10096
	v_fma_f32 v36, -v125, v51, v36
	v_fma_f32 v4, v125, v19, v4
	v_fmac_f32_e32 v36, v124, v19
	v_fmac_f32_e32 v4, v124, v51
	v_cvt_pk_bf16_f32 v154, v36, v4
	ds_write_b32 v150, v154 offset:10368
	v_fma_f32 v37, -v125, v4, v37
	v_fma_f32 v5, v125, v36, v5
	v_fmac_f32_e32 v37, v124, v36
	v_fmac_f32_e32 v5, v124, v4
	v_cvt_pk_bf16_f32 v154, v37, v5
	ds_write_b32 v150, v154 offset:10640
	v_fma_f32 v38, -v125, v5, v38
	v_fma_f32 v6, v125, v37, v6
	v_fmac_f32_e32 v38, v124, v37
	v_fmac_f32_e32 v6, v124, v5
	v_cvt_pk_bf16_f32 v154, v38, v6
	ds_write_b32 v150, v154 offset:10912
	v_fma_f32 v39, -v125, v6, v39
	v_fma_f32 v7, v125, v38, v7
	v_fmac_f32_e32 v39, v124, v38
	v_fmac_f32_e32 v7, v124, v6
	v_cvt_pk_bf16_f32 v154, v39, v7
	ds_write_b32 v150, v154 offset:11184
	v_fma_f32 v20, -v125, v7, v20
	v_fma_f32 v52, v125, v39, v52
	v_fmac_f32_e32 v20, v124, v39
	v_fmac_f32_e32 v52, v124, v7
	v_cvt_pk_bf16_f32 v154, v20, v52
	ds_write_b32 v150, v154 offset:11456
	v_fma_f32 v21, -v125, v52, v21
	v_fma_f32 v53, v125, v20, v53
	v_fmac_f32_e32 v21, v124, v20
	v_fmac_f32_e32 v53, v124, v52
	v_cvt_pk_bf16_f32 v154, v21, v53
	ds_write_b32 v150, v154 offset:11728
	v_fma_f32 v22, -v125, v53, v22
	v_fma_f32 v54, v125, v21, v54
	v_fmac_f32_e32 v22, v124, v21
	v_fmac_f32_e32 v54, v124, v53
	v_cvt_pk_bf16_f32 v154, v22, v54
	ds_write_b32 v150, v154 offset:12000
	v_fma_f32 v23, -v125, v54, v23
	v_fma_f32 v55, v125, v22, v55
	v_fmac_f32_e32 v23, v124, v22
	v_fmac_f32_e32 v55, v124, v54
	v_cvt_pk_bf16_f32 v154, v23, v55
	ds_write_b32 v150, v154 offset:12272
	v_fma_f32 v40, -v125, v55, v40
	v_fma_f32 v8, v125, v23, v8
	v_fmac_f32_e32 v40, v124, v23
	v_fmac_f32_e32 v8, v124, v55
	v_cvt_pk_bf16_f32 v154, v40, v8
	ds_write_b32 v150, v154 offset:12544
	v_fma_f32 v41, -v125, v8, v41
	v_fma_f32 v9, v125, v40, v9
	v_fmac_f32_e32 v41, v124, v40
	v_fmac_f32_e32 v9, v124, v8
	v_cvt_pk_bf16_f32 v154, v41, v9
	ds_write_b32 v150, v154 offset:12816
	v_fma_f32 v42, -v125, v9, v42
	v_fma_f32 v10, v125, v41, v10
	v_fmac_f32_e32 v42, v124, v41
	v_fmac_f32_e32 v10, v124, v9
	v_cvt_pk_bf16_f32 v154, v42, v10
	ds_write_b32 v150, v154 offset:13088
	v_fma_f32 v43, -v125, v10, v43
	v_fma_f32 v11, v125, v42, v11
	v_fmac_f32_e32 v43, v124, v42
	v_fmac_f32_e32 v11, v124, v10
	v_cvt_pk_bf16_f32 v154, v43, v11
	ds_write_b32 v150, v154 offset:13360
	v_fma_f32 v24, -v125, v11, v24
	v_fma_f32 v56, v125, v43, v56
	v_fmac_f32_e32 v24, v124, v43
	v_fmac_f32_e32 v56, v124, v11
	v_cvt_pk_bf16_f32 v154, v24, v56
	ds_write_b32 v150, v154 offset:13632
	v_fma_f32 v25, -v125, v56, v25
	v_fma_f32 v57, v125, v24, v57
	v_fmac_f32_e32 v25, v124, v24
	v_fmac_f32_e32 v57, v124, v56
	v_cvt_pk_bf16_f32 v154, v25, v57
	ds_write_b32 v150, v154 offset:13904
	v_fma_f32 v26, -v125, v57, v26
	v_fma_f32 v58, v125, v25, v58
	v_fmac_f32_e32 v26, v124, v25
	v_fmac_f32_e32 v58, v124, v57
	v_cvt_pk_bf16_f32 v154, v26, v58
	ds_write_b32 v150, v154 offset:14176
	v_fma_f32 v27, -v125, v58, v27
	v_fma_f32 v59, v125, v26, v59
	v_fmac_f32_e32 v27, v124, v26
	v_fmac_f32_e32 v59, v124, v58
	v_cvt_pk_bf16_f32 v154, v27, v59
	ds_write_b32 v150, v154 offset:14448
	v_fma_f32 v44, -v125, v59, v44
	v_fma_f32 v12, v125, v27, v12
	v_fmac_f32_e32 v44, v124, v27
	v_fmac_f32_e32 v12, v124, v59
	v_cvt_pk_bf16_f32 v154, v44, v12
	ds_write_b32 v150, v154 offset:14720
	v_fma_f32 v45, -v125, v12, v45
	v_fma_f32 v13, v125, v44, v13
	v_fmac_f32_e32 v45, v124, v44
	v_fmac_f32_e32 v13, v124, v12
	v_cvt_pk_bf16_f32 v154, v45, v13
	ds_write_b32 v150, v154 offset:14992
	v_fma_f32 v46, -v125, v13, v46
	v_fma_f32 v14, v125, v45, v14
	v_fmac_f32_e32 v46, v124, v45
	v_fmac_f32_e32 v14, v124, v13
	v_cvt_pk_bf16_f32 v154, v46, v14
	ds_write_b32 v150, v154 offset:15264
	v_fma_f32 v47, -v125, v14, v47
	v_fma_f32 v15, v125, v46, v15
	v_fmac_f32_e32 v47, v124, v46
	v_fmac_f32_e32 v15, v124, v14
	v_cvt_pk_bf16_f32 v154, v47, v15
	ds_write_b32 v150, v154 offset:15536
	v_fma_f32 v28, -v125, v15, v28
	v_fma_f32 v60, v125, v47, v60
	v_fmac_f32_e32 v28, v124, v47
	v_fmac_f32_e32 v60, v124, v15
	v_cvt_pk_bf16_f32 v154, v28, v60
	ds_write_b32 v150, v154 offset:15808
	v_fma_f32 v29, -v125, v60, v29
	v_fma_f32 v61, v125, v28, v61
	v_fmac_f32_e32 v29, v124, v28
	v_fmac_f32_e32 v61, v124, v60
	v_cvt_pk_bf16_f32 v154, v29, v61
	ds_write_b32 v150, v154 offset:16080
	v_fma_f32 v30, -v125, v61, v30
	v_fma_f32 v62, v125, v29, v62
	v_fmac_f32_e32 v30, v124, v29
	v_fmac_f32_e32 v62, v124, v61
	v_cvt_pk_bf16_f32 v154, v30, v62
	ds_write_b32 v150, v154 offset:16352
	v_fma_f32 v143, -v125, v62, v31
	v_fma_f32 v142, v125, v30, v63
	v_fmac_f32_e32 v143, v124, v30
	v_fmac_f32_e32 v142, v124, v62
	v_cvt_pk_bf16_f32 v154, v143, v142
	ds_write_b32 v150, v154 offset:16624
	ds_read_b128 v[16:19], v151 offset:8192
	ds_read_b128 v[20:23], v151 offset:8224
	ds_read_b128 v[24:27], v151 offset:8256
	ds_read_b128 v[28:31], v151 offset:8288
	ds_read_b128 v[32:35], v151 offset:8320
	ds_read_b128 v[36:39], v151 offset:8352
	ds_read_b128 v[40:43], v151 offset:8384
	ds_read_b128 v[44:47], v151 offset:8416
	s_waitcnt lgkmcnt(7)
	v_mfma_f32_32x32x16_bf16 v[0:15], v[84:87], v[16:19], 0
	s_waitcnt lgkmcnt(6)
	v_mfma_f32_32x32x16_bf16 v[0:15], v[80:83], v[20:23], v[0:15]
	s_waitcnt lgkmcnt(5)
	v_mfma_f32_32x32x16_bf16 v[0:15], v[88:91], v[24:27], v[0:15]
	s_waitcnt lgkmcnt(4)
	v_mfma_f32_32x32x16_bf16 v[0:15], v[92:95], v[28:31], v[0:15]
	s_waitcnt lgkmcnt(3)
	v_mfma_f32_32x32x16_bf16 v[0:15], v[96:99], v[32:35], v[0:15]
	s_waitcnt lgkmcnt(2)
	v_mfma_f32_32x32x16_bf16 v[0:15], v[100:103], v[36:39], v[0:15]
	s_waitcnt lgkmcnt(1)
	v_mfma_f32_32x32x16_bf16 v[0:15], v[104:107], v[40:43], v[0:15]
	s_waitcnt lgkmcnt(0)
	v_mfma_f32_32x32x16_bf16 v[0:15], v[108:111], v[44:47], v[0:15]
	s_nop 10
	v_and_b32_e32 v9, 0xffff0000, v140
	v_lshlrev_b32_e32 v10, 16, v141
	v_fma_f32 v1, v113, v9, v1
	v_fma_f32 v2, v114, v10, v2
	v_mul_f32_e32 v9, v1, v1
	v_mul_f32_e32 v10, v2, v2
	v_fmamk_f32 v9, v9, 0xbdd2d3e8, v246
	v_fmamk_f32 v10, v10, 0xbdd2d3e8, v246
	v_lshlrev_b32_e32 v8, 16, v140
	v_mul_f32_e32 v9, v1, v9
	v_mul_f32_e32 v10, v2, v10
	v_fma_f32 v0, v112, v8, v0
	v_exp_f32_e32 v9, v9
	v_exp_f32_e32 v10, v10
	v_mul_f32_e32 v8, v0, v0
	v_fmamk_f32 v8, v8, 0xbdd2d3e8, v246
	v_mul_f32_e32 v8, v0, v8
	v_exp_f32_e32 v8, v8
	v_add_f32_e32 v9, 1.0, v9
	v_add_f32_e32 v10, 1.0, v10
	v_and_b32_e32 v11, 0xffff0000, v141
	v_rcp_f32_e32 v9, v9
	v_rcp_f32_e32 v10, v10
	v_fma_f32 v3, v115, v11, v3
	v_mul_f32_e32 v11, v3, v3
	v_fmamk_f32 v11, v11, 0xbdd2d3e8, v246
	v_add_f32_e32 v8, 1.0, v8
	v_mul_f32_e32 v11, v3, v11
	v_rcp_f32_e32 v8, v8
	v_exp_f32_e32 v11, v11
	v_mul_f32_e32 v1, v1, v9
	v_mul_f32_e32 v2, v2, v10
	v_lshlrev_b32_e32 v9, 16, v138
	v_and_b32_e32 v10, 0xffff0000, v138
	v_fma_f32 v4, v116, v9, v4
	v_fma_f32 v5, v117, v10, v5
	v_mul_f32_e32 v9, v4, v4
	v_mul_f32_e32 v10, v5, v5
	v_fmamk_f32 v9, v9, 0xbdd2d3e8, v246
	v_fmamk_f32 v10, v10, 0xbdd2d3e8, v246
	v_mul_f32_e32 v0, v0, v8
	v_add_f32_e32 v8, 1.0, v11
	v_mul_f32_e32 v9, v4, v9
	v_mul_f32_e32 v10, v5, v10
	v_rcp_f32_e32 v8, v8
	v_exp_f32_e32 v9, v9
	v_exp_f32_e32 v10, v10
	v_and_b32_e32 v11, 0xffff0000, v139
	v_mul_f32_e32 v3, v3, v8
	v_add_f32_e32 v8, 1.0, v9
	v_add_f32_e32 v9, 1.0, v10
	v_lshlrev_b32_e32 v10, 16, v139
	v_fma_f32 v6, v118, v10, v6
	v_fmac_f32_e32 v7, v119, v11
	v_mul_f32_e32 v10, v6, v6
	v_mul_f32_e32 v11, v7, v7
	v_fmamk_f32 v10, v10, 0xbdd2d3e8, v246
	v_fmamk_f32 v11, v11, 0xbdd2d3e8, v246
	v_mul_f32_e32 v10, v6, v10
	v_mul_f32_e32 v11, v7, v11
	v_exp_f32_e32 v10, v10
	v_exp_f32_e32 v11, v11
	v_rcp_f32_e32 v8, v8
	v_rcp_f32_e32 v9, v9
	v_add_f32_e32 v10, 1.0, v10
	v_add_f32_e32 v11, 1.0, v11
	v_rcp_f32_e32 v10, v10
	v_rcp_f32_e32 v11, v11
	v_cvt_pk_bf16_f32 v0, v0, v1
	v_cvt_pk_bf16_f32 v1, v2, v3
	v_add_co_u32_e32 v2, vcc, s4, v136
	v_mul_f32_e32 v4, v4, v8
	s_nop 0
	v_addc_co_u32_e32 v3, vcc, 0, v137, vcc
	v_mul_f32_e32 v5, v5, v9
	v_mul_f32_e32 v6, v6, v10
	v_mul_f32_e32 v7, v7, v11
	global_store_dwordx2 v[2:3], v[0:1], off
	v_cvt_pk_bf16_f32 v0, v4, v5
	v_cvt_pk_bf16_f32 v1, v6, v7
	global_store_dwordx2 v[2:3], v[0:1], off offset:16
	s_cbranch_scc0 .LBB0_924
